# layer-1 output-projection epilogue: x and d0 loads batched 4 blocks per round trip instead of one wait per 4 columns
# speedup vs baseline: 1.0131x; 1.0131x over previous
; __device__ __forceinline__ float bflo(unsigned w) { return __uint_as_float(w << 16); }
; __device__ __forceinline__ float bfhi(unsigned w) { return __uint_as_float(w & 0xffff0000u); }
;     __device__ __forceinline__ void store4(int row, int col, const f32x4 v) const { __builtin_nontemporal_store(pk4(v), (u32x2*)((bf16_t*)((unsigned char*)out + T_D0) + (size_t)row * DM + col)); }
;     __device__ __forceinline__ void store8(int row, int col, const f32x4 v, const f32x4 w) const { st8_bf16((bf16_t*)((unsigned char*)out + T_D0) + (size_t)row * DM + col, v, w); }
; #define EA_M(ai, bj) EA_BLK(ai, bj, 0) EA_BLK(ai, bj, 1) EA_BLK(ai, bj, 2) EA_BLK(ai, bj, 3)
;     __device__ __forceinline__ void store4(int row, int col, const f32x4 v) const {
;         const f32x4 x = row < MP ? *(const f32x4*)(xp + (size_t)row * DM + col) : *(const f32x4*)(xs + (size_t)(row - MP) * DM + col);
;         const u32x2 d = *(const u32x2*)((const bf16_t*)((const unsigned char*)out + T_D0) + (size_t)row * DM + col);
;         const f32x4 d0 = {bflo(d.x), bfhi(d.x), bflo(d.y), bfhi(d.y)};
;         __builtin_nontemporal_store(x + d0 + v, (f32x4*)((float*)(ws + WS_X2) + (size_t)row * DM + col));
;     }
;     __device__ __forceinline__ void store8(int row, int col, const f32x4 v, const f32x4 w) const { store4(row, col, v); store4(row, col + 4, w); }
;     __device__ __forceinline__ void operator()(const pg8::f32x4 (&acc)[2][2][4][2], const pg8::Unit& u, int wr, int wc, int fr, int fq) const {
;     ...
;         const int row0 = u.pm * 256 + wr * 64 + fr, col0 = u.pn * 256 + wc * 32 + 8 * fq;
;     ...
;         EA_M(0, 0) EA_M(0, 1) EA_M(1, 0) EA_M(1, 1)
.LBB0_1234:
	s_lshl_b32 s84, s6, 20
	s_lshl_b32 s85, s4, 10
	s_cmp_lt_u32 s6, 0x100
	s_cselect_b32 s86, s16, s18
	s_cselect_b32 s87, s17, s19
	s_cselect_b32 s88, 0, 0x10000000
	s_sub_u32 s88, s84, s88
	s_add_u32 s86, s86, s88
	s_addc_u32 s87, s87, 0
	s_add_u32 s86, s86, s85
	s_addc_u32 s87, s87, 0
	s_add_u32 s88, s14, 0x25ce0000
	s_addc_u32 s89, s15, 0
	s_add_u32 s88, s88, s84
	s_addc_u32 s89, s89, 0
	s_add_u32 s88, s88, s85
	s_addc_u32 s89, s89, 0
	s_lshr_b32 s90, s84, 1
	s_lshr_b32 s91, s85, 1
	s_add_u32 s92, s12, 0x8100000
	s_addc_u32 s93, s13, 0
	s_add_u32 s92, s92, s90
	s_addc_u32 s93, s93, 0
	s_add_u32 s92, s92, s91
	s_addc_u32 s93, s93, 0
	v_lshlrev_b32_e32 v146, 12, v154
	v_lshl_add_u32 v146, v156, 2, v146
	v_mov_b32_e32 v224, v146
	v_lshrrev_b32_e32 v228, 1, v224
	global_load_dwordx4 v[176:179], v224, s[86:87]
	global_load_dwordx4 v[180:183], v224, s[86:87] offset:16
	global_load_dwordx4 v[208:211], v228, s[92:93]
	v_add_u32_e32 v225, 0x10000, v146
	v_lshrrev_b32_e32 v229, 1, v225
	global_load_dwordx4 v[184:187], v225, s[86:87]
	global_load_dwordx4 v[188:191], v225, s[86:87] offset:16
	global_load_dwordx4 v[212:215], v229, s[92:93]
	v_add_u32_e32 v226, 0x20000, v146
	v_lshrrev_b32_e32 v230, 1, v226
	global_load_dwordx4 v[192:195], v226, s[86:87]
	global_load_dwordx4 v[196:199], v226, s[86:87] offset:16
	global_load_dwordx4 v[216:219], v230, s[92:93]
	v_add_u32_e32 v227, 0x30000, v146
	v_lshrrev_b32_e32 v231, 1, v227
	global_load_dwordx4 v[200:203], v227, s[86:87]
	global_load_dwordx4 v[204:207], v227, s[86:87] offset:16
	global_load_dwordx4 v[220:223], v231, s[92:93]
	s_waitcnt vmcnt(0)
	v_lshlrev_b32_e32 v232, 16, v208
	v_and_b32_e32 v233, 0xffff0000, v208
	v_pk_add_f32 v[176:177], v[176:177], v[232:233]
	v_pk_add_f32 v[124:125], v[124:125], v[176:177]
	v_lshlrev_b32_e32 v232, 16, v209
	v_and_b32_e32 v233, 0xffff0000, v209
	v_pk_add_f32 v[178:179], v[178:179], v[232:233]
	v_pk_add_f32 v[126:127], v[126:127], v[178:179]
	v_lshlrev_b32_e32 v232, 16, v210
	v_and_b32_e32 v233, 0xffff0000, v210
	v_pk_add_f32 v[180:181], v[180:181], v[232:233]
	v_pk_add_f32 v[120:121], v[120:121], v[180:181]
	v_lshlrev_b32_e32 v232, 16, v211
	v_and_b32_e32 v233, 0xffff0000, v211
	v_pk_add_f32 v[182:183], v[182:183], v[232:233]
	v_pk_add_f32 v[122:123], v[122:123], v[182:183]
	global_store_dwordx4 v224, v[124:127], s[88:89] nt
	global_store_dwordx4 v224, v[120:123], s[88:89] offset:16 nt
	v_lshlrev_b32_e32 v232, 16, v212
	v_and_b32_e32 v233, 0xffff0000, v212
	v_pk_add_f32 v[184:185], v[184:185], v[232:233]
	v_pk_add_f32 v[116:117], v[116:117], v[184:185]
	v_lshlrev_b32_e32 v232, 16, v213
	v_and_b32_e32 v233, 0xffff0000, v213
	v_pk_add_f32 v[186:187], v[186:187], v[232:233]
	v_pk_add_f32 v[118:119], v[118:119], v[186:187]
	v_lshlrev_b32_e32 v232, 16, v214
	v_and_b32_e32 v233, 0xffff0000, v214
	v_pk_add_f32 v[188:189], v[188:189], v[232:233]
	v_pk_add_f32 v[112:113], v[112:113], v[188:189]
	v_lshlrev_b32_e32 v232, 16, v215
	v_and_b32_e32 v233, 0xffff0000, v215
	v_pk_add_f32 v[190:191], v[190:191], v[232:233]
	v_pk_add_f32 v[114:115], v[114:115], v[190:191]
	global_store_dwordx4 v225, v[116:119], s[88:89] nt
	global_store_dwordx4 v225, v[112:115], s[88:89] offset:16 nt
	v_lshlrev_b32_e32 v232, 16, v216
	v_and_b32_e32 v233, 0xffff0000, v216
	v_pk_add_f32 v[192:193], v[192:193], v[232:233]
	v_pk_add_f32 v[108:109], v[108:109], v[192:193]
	v_lshlrev_b32_e32 v232, 16, v217
	v_and_b32_e32 v233, 0xffff0000, v217
	v_pk_add_f32 v[194:195], v[194:195], v[232:233]
	v_pk_add_f32 v[110:111], v[110:111], v[194:195]
	v_lshlrev_b32_e32 v232, 16, v218
	v_and_b32_e32 v233, 0xffff0000, v218
	v_pk_add_f32 v[196:197], v[196:197], v[232:233]
	v_pk_add_f32 v[104:105], v[104:105], v[196:197]
	v_lshlrev_b32_e32 v232, 16, v219
	v_and_b32_e32 v233, 0xffff0000, v219
	v_pk_add_f32 v[198:199], v[198:199], v[232:233]
	v_pk_add_f32 v[106:107], v[106:107], v[198:199]
	global_store_dwordx4 v226, v[108:111], s[88:89] nt
	global_store_dwordx4 v226, v[104:107], s[88:89] offset:16 nt
	v_lshlrev_b32_e32 v232, 16, v220
	v_and_b32_e32 v233, 0xffff0000, v220
	v_pk_add_f32 v[200:201], v[200:201], v[232:233]
	v_pk_add_f32 v[100:101], v[100:101], v[200:201]
	v_lshlrev_b32_e32 v232, 16, v221
	v_and_b32_e32 v233, 0xffff0000, v221
	v_pk_add_f32 v[202:203], v[202:203], v[232:233]
	v_pk_add_f32 v[102:103], v[102:103], v[202:203]
	v_lshlrev_b32_e32 v232, 16, v222
	v_and_b32_e32 v233, 0xffff0000, v222
	v_pk_add_f32 v[204:205], v[204:205], v[232:233]
	v_pk_add_f32 v[96:97], v[96:97], v[204:205]
	v_lshlrev_b32_e32 v232, 16, v223
	v_and_b32_e32 v233, 0xffff0000, v223
	v_pk_add_f32 v[206:207], v[206:207], v[232:233]
	v_pk_add_f32 v[98:99], v[98:99], v[206:207]
	global_store_dwordx4 v227, v[100:103], s[88:89] nt
	global_store_dwordx4 v227, v[96:99], s[88:89] offset:16 nt
	v_add_u32_e32 v224, 0x200, v146
	v_lshrrev_b32_e32 v228, 1, v224
	global_load_dwordx4 v[176:179], v224, s[86:87]
	global_load_dwordx4 v[180:183], v224, s[86:87] offset:16
	global_load_dwordx4 v[208:211], v228, s[92:93]
	v_add_u32_e32 v225, 0x10200, v146
	v_lshrrev_b32_e32 v229, 1, v225
	global_load_dwordx4 v[184:187], v225, s[86:87]
	global_load_dwordx4 v[188:191], v225, s[86:87] offset:16
	global_load_dwordx4 v[212:215], v229, s[92:93]
	v_add_u32_e32 v226, 0x20200, v146
	v_lshrrev_b32_e32 v230, 1, v226
	global_load_dwordx4 v[192:195], v226, s[86:87]
	global_load_dwordx4 v[196:199], v226, s[86:87] offset:16
	global_load_dwordx4 v[216:219], v230, s[92:93]
	v_add_u32_e32 v227, 0x30200, v146
	v_lshrrev_b32_e32 v231, 1, v227
	global_load_dwordx4 v[200:203], v227, s[86:87]
	global_load_dwordx4 v[204:207], v227, s[86:87] offset:16
	global_load_dwordx4 v[220:223], v231, s[92:93]
	s_waitcnt vmcnt(0)
; __device__ __forceinline__ float bflo(unsigned w) { return __uint_as_float(w << 16); }
; __device__ __forceinline__ float bfhi(unsigned w) { return __uint_as_float(w & 0xffff0000u); }
;     __device__ __forceinline__ void store4(int row, int col, const f32x4 v) const { __builtin_nontemporal_store(pk4(v), (u32x2*)((bf16_t*)((unsigned char*)out + T_D0) + (size_t)row * DM + col)); }
;     __device__ __forceinline__ void store8(int row, int col, const f32x4 v, const f32x4 w) const { st8_bf16((bf16_t*)((unsigned char*)out + T_D0) + (size_t)row * DM + col, v, w); }
; #define EA_M(ai, bj) EA_BLK(ai, bj, 0) EA_BLK(ai, bj, 1) EA_BLK(ai, bj, 2) EA_BLK(ai, bj, 3)
;     __device__ __forceinline__ void store4(int row, int col, const f32x4 v) const {
;         const f32x4 x = row < MP ? *(const f32x4*)(xp + (size_t)row * DM + col) : *(const f32x4*)(xs + (size_t)(row - MP) * DM + col);
;         const u32x2 d = *(const u32x2*)((const bf16_t*)((const unsigned char*)out + T_D0) + (size_t)row * DM + col);
;         const f32x4 d0 = {bflo(d.x), bfhi(d.x), bflo(d.y), bfhi(d.y)};
;         __builtin_nontemporal_store(x + d0 + v, (f32x4*)((float*)(ws + WS_X2) + (size_t)row * DM + col));
;     }
;     __device__ __forceinline__ void store8(int row, int col, const f32x4 v, const f32x4 w) const { store4(row, col, v); store4(row, col + 4, w); }
;     __device__ __forceinline__ void operator()(const pg8::f32x4 (&acc)[2][2][4][2], const pg8::Unit& u, int wr, int wc, int fr, int fq) const {
;     ...
;         const int row0 = u.pm * 256 + wr * 64 + fr, col0 = u.pn * 256 + wc * 32 + 8 * fq;
;     ...
;         EA_M(0, 0) EA_M(0, 1) EA_M(1, 0) EA_M(1, 1)
	v_lshlrev_b32_e32 v232, 16, v208
	v_and_b32_e32 v233, 0xffff0000, v208
	v_pk_add_f32 v[176:177], v[176:177], v[232:233]
	v_pk_add_f32 v[92:93], v[92:93], v[176:177]
	v_lshlrev_b32_e32 v232, 16, v209
	v_and_b32_e32 v233, 0xffff0000, v209
	v_pk_add_f32 v[178:179], v[178:179], v[232:233]
	v_pk_add_f32 v[94:95], v[94:95], v[178:179]
	v_lshlrev_b32_e32 v232, 16, v210
	v_and_b32_e32 v233, 0xffff0000, v210
	v_pk_add_f32 v[180:181], v[180:181], v[232:233]
	v_pk_add_f32 v[88:89], v[88:89], v[180:181]
	v_lshlrev_b32_e32 v232, 16, v211
	v_and_b32_e32 v233, 0xffff0000, v211
	v_pk_add_f32 v[182:183], v[182:183], v[232:233]
	v_pk_add_f32 v[90:91], v[90:91], v[182:183]
	global_store_dwordx4 v224, v[92:95], s[88:89] nt
	global_store_dwordx4 v224, v[88:91], s[88:89] offset:16 nt
	v_lshlrev_b32_e32 v232, 16, v212
	v_and_b32_e32 v233, 0xffff0000, v212
	v_pk_add_f32 v[184:185], v[184:185], v[232:233]
	v_pk_add_f32 v[84:85], v[84:85], v[184:185]
	v_lshlrev_b32_e32 v232, 16, v213
	v_and_b32_e32 v233, 0xffff0000, v213
	v_pk_add_f32 v[186:187], v[186:187], v[232:233]
	v_pk_add_f32 v[86:87], v[86:87], v[186:187]
	v_lshlrev_b32_e32 v232, 16, v214
	v_and_b32_e32 v233, 0xffff0000, v214
	v_pk_add_f32 v[188:189], v[188:189], v[232:233]
	v_pk_add_f32 v[80:81], v[80:81], v[188:189]
	v_lshlrev_b32_e32 v232, 16, v215
	v_and_b32_e32 v233, 0xffff0000, v215
	v_pk_add_f32 v[190:191], v[190:191], v[232:233]
	v_pk_add_f32 v[82:83], v[82:83], v[190:191]
	global_store_dwordx4 v225, v[84:87], s[88:89] nt
	global_store_dwordx4 v225, v[80:83], s[88:89] offset:16 nt
	v_lshlrev_b32_e32 v232, 16, v216
	v_and_b32_e32 v233, 0xffff0000, v216
	v_pk_add_f32 v[192:193], v[192:193], v[232:233]
	v_pk_add_f32 v[76:77], v[76:77], v[192:193]
	v_lshlrev_b32_e32 v232, 16, v217
	v_and_b32_e32 v233, 0xffff0000, v217
	v_pk_add_f32 v[194:195], v[194:195], v[232:233]
	v_pk_add_f32 v[78:79], v[78:79], v[194:195]
	v_lshlrev_b32_e32 v232, 16, v218
	v_and_b32_e32 v233, 0xffff0000, v218
	v_pk_add_f32 v[196:197], v[196:197], v[232:233]
	v_pk_add_f32 v[72:73], v[72:73], v[196:197]
	v_lshlrev_b32_e32 v232, 16, v219
	v_and_b32_e32 v233, 0xffff0000, v219
	v_pk_add_f32 v[198:199], v[198:199], v[232:233]
	v_pk_add_f32 v[74:75], v[74:75], v[198:199]
	global_store_dwordx4 v226, v[76:79], s[88:89] nt
	global_store_dwordx4 v226, v[72:75], s[88:89] offset:16 nt
	v_lshlrev_b32_e32 v232, 16, v220
	v_and_b32_e32 v233, 0xffff0000, v220
	v_pk_add_f32 v[200:201], v[200:201], v[232:233]
	v_pk_add_f32 v[68:69], v[68:69], v[200:201]
	v_lshlrev_b32_e32 v232, 16, v221
	v_and_b32_e32 v233, 0xffff0000, v221
	v_pk_add_f32 v[202:203], v[202:203], v[232:233]
	v_pk_add_f32 v[70:71], v[70:71], v[202:203]
	v_lshlrev_b32_e32 v232, 16, v222
	v_and_b32_e32 v233, 0xffff0000, v222
	v_pk_add_f32 v[204:205], v[204:205], v[232:233]
	v_pk_add_f32 v[64:65], v[64:65], v[204:205]
	v_lshlrev_b32_e32 v232, 16, v223
	v_and_b32_e32 v233, 0xffff0000, v223
	v_pk_add_f32 v[206:207], v[206:207], v[232:233]
	v_pk_add_f32 v[66:67], v[66:67], v[206:207]
	global_store_dwordx4 v227, v[68:71], s[88:89] nt
	global_store_dwordx4 v227, v[64:67], s[88:89] offset:16 nt
	v_add_u32_e32 v224, 0x80000, v146
	v_lshrrev_b32_e32 v228, 1, v224
	global_load_dwordx4 v[176:179], v224, s[86:87]
	global_load_dwordx4 v[180:183], v224, s[86:87] offset:16
	global_load_dwordx4 v[208:211], v228, s[92:93]
	v_add_u32_e32 v225, 0x90000, v146
	v_lshrrev_b32_e32 v229, 1, v225
	global_load_dwordx4 v[184:187], v225, s[86:87]
	global_load_dwordx4 v[188:191], v225, s[86:87] offset:16
	global_load_dwordx4 v[212:215], v229, s[92:93]
	v_add_u32_e32 v226, 0xa0000, v146
	v_lshrrev_b32_e32 v230, 1, v226
	global_load_dwordx4 v[192:195], v226, s[86:87]
	global_load_dwordx4 v[196:199], v226, s[86:87] offset:16
	global_load_dwordx4 v[216:219], v230, s[92:93]
	v_add_u32_e32 v227, 0xb0000, v146
	v_lshrrev_b32_e32 v231, 1, v227
	global_load_dwordx4 v[200:203], v227, s[86:87]
	global_load_dwordx4 v[204:207], v227, s[86:87] offset:16
	global_load_dwordx4 v[220:223], v231, s[92:93]
	s_waitcnt vmcnt(0)
	v_lshlrev_b32_e32 v232, 16, v208
	v_and_b32_e32 v233, 0xffff0000, v208
	v_pk_add_f32 v[176:177], v[176:177], v[232:233]
	v_pk_add_f32 v[60:61], v[60:61], v[176:177]
	v_lshlrev_b32_e32 v232, 16, v209
	v_and_b32_e32 v233, 0xffff0000, v209
	v_pk_add_f32 v[178:179], v[178:179], v[232:233]
	v_pk_add_f32 v[62:63], v[62:63], v[178:179]
	v_lshlrev_b32_e32 v232, 16, v210
	v_and_b32_e32 v233, 0xffff0000, v210
	v_pk_add_f32 v[180:181], v[180:181], v[232:233]
	v_pk_add_f32 v[56:57], v[56:57], v[180:181]
	v_lshlrev_b32_e32 v232, 16, v211
	v_and_b32_e32 v233, 0xffff0000, v211
	v_pk_add_f32 v[182:183], v[182:183], v[232:233]
	v_pk_add_f32 v[58:59], v[58:59], v[182:183]
	global_store_dwordx4 v224, v[60:63], s[88:89] nt
	global_store_dwordx4 v224, v[56:59], s[88:89] offset:16 nt
	v_lshlrev_b32_e32 v232, 16, v212
	v_and_b32_e32 v233, 0xffff0000, v212
	v_pk_add_f32 v[184:185], v[184:185], v[232:233]
	v_pk_add_f32 v[52:53], v[52:53], v[184:185]
	v_lshlrev_b32_e32 v232, 16, v213
	v_and_b32_e32 v233, 0xffff0000, v213
	v_pk_add_f32 v[186:187], v[186:187], v[232:233]
	v_pk_add_f32 v[54:55], v[54:55], v[186:187]
	v_lshlrev_b32_e32 v232, 16, v214
	v_and_b32_e32 v233, 0xffff0000, v214
	v_pk_add_f32 v[188:189], v[188:189], v[232:233]
	v_pk_add_f32 v[48:49], v[48:49], v[188:189]
	v_lshlrev_b32_e32 v232, 16, v215
	v_and_b32_e32 v233, 0xffff0000, v215
	v_pk_add_f32 v[190:191], v[190:191], v[232:233]
	v_pk_add_f32 v[50:51], v[50:51], v[190:191]
	global_store_dwordx4 v225, v[52:55], s[88:89] nt
	global_store_dwordx4 v225, v[48:51], s[88:89] offset:16 nt
	v_lshlrev_b32_e32 v232, 16, v216
	v_and_b32_e32 v233, 0xffff0000, v216
; __device__ __forceinline__ float bflo(unsigned w) { return __uint_as_float(w << 16); }
; __device__ __forceinline__ float bfhi(unsigned w) { return __uint_as_float(w & 0xffff0000u); }
;     __device__ __forceinline__ void store4(int row, int col, const f32x4 v) const { __builtin_nontemporal_store(pk4(v), (u32x2*)((bf16_t*)((unsigned char*)out + T_D0) + (size_t)row * DM + col)); }
;     __device__ __forceinline__ void store8(int row, int col, const f32x4 v, const f32x4 w) const { st8_bf16((bf16_t*)((unsigned char*)out + T_D0) + (size_t)row * DM + col, v, w); }
; #define EA_M(ai, bj) EA_BLK(ai, bj, 0) EA_BLK(ai, bj, 1) EA_BLK(ai, bj, 2) EA_BLK(ai, bj, 3)
;     __device__ __forceinline__ void store4(int row, int col, const f32x4 v) const {
;         const f32x4 x = row < MP ? *(const f32x4*)(xp + (size_t)row * DM + col) : *(const f32x4*)(xs + (size_t)(row - MP) * DM + col);
;         const u32x2 d = *(const u32x2*)((const bf16_t*)((const unsigned char*)out + T_D0) + (size_t)row * DM + col);
;         const f32x4 d0 = {bflo(d.x), bfhi(d.x), bflo(d.y), bfhi(d.y)};
;         __builtin_nontemporal_store(x + d0 + v, (f32x4*)((float*)(ws + WS_X2) + (size_t)row * DM + col));
;     }
;     __device__ __forceinline__ void store8(int row, int col, const f32x4 v, const f32x4 w) const { store4(row, col, v); store4(row, col + 4, w); }
;     __device__ __forceinline__ void operator()(const pg8::f32x4 (&acc)[2][2][4][2], const pg8::Unit& u, int wr, int wc, int fr, int fq) const {
;     ...
;         const int row0 = u.pm * 256 + wr * 64 + fr, col0 = u.pn * 256 + wc * 32 + 8 * fq;
;     ...
;         EA_M(0, 0) EA_M(0, 1) EA_M(1, 0) EA_M(1, 1)
	v_pk_add_f32 v[192:193], v[192:193], v[232:233]
	v_pk_add_f32 v[44:45], v[44:45], v[192:193]
	v_lshlrev_b32_e32 v232, 16, v217
	v_and_b32_e32 v233, 0xffff0000, v217
	v_pk_add_f32 v[194:195], v[194:195], v[232:233]
	v_pk_add_f32 v[46:47], v[46:47], v[194:195]
	v_lshlrev_b32_e32 v232, 16, v218
	v_and_b32_e32 v233, 0xffff0000, v218
	v_pk_add_f32 v[196:197], v[196:197], v[232:233]
	v_pk_add_f32 v[40:41], v[40:41], v[196:197]
	v_lshlrev_b32_e32 v232, 16, v219
	v_and_b32_e32 v233, 0xffff0000, v219
	v_pk_add_f32 v[198:199], v[198:199], v[232:233]
	v_pk_add_f32 v[42:43], v[42:43], v[198:199]
	global_store_dwordx4 v226, v[44:47], s[88:89] nt
	global_store_dwordx4 v226, v[40:43], s[88:89] offset:16 nt
	v_lshlrev_b32_e32 v232, 16, v220
	v_and_b32_e32 v233, 0xffff0000, v220
	v_pk_add_f32 v[200:201], v[200:201], v[232:233]
	v_pk_add_f32 v[36:37], v[36:37], v[200:201]
	v_lshlrev_b32_e32 v232, 16, v221
	v_and_b32_e32 v233, 0xffff0000, v221
	v_pk_add_f32 v[202:203], v[202:203], v[232:233]
	v_pk_add_f32 v[38:39], v[38:39], v[202:203]
	v_lshlrev_b32_e32 v232, 16, v222
	v_and_b32_e32 v233, 0xffff0000, v222
	v_pk_add_f32 v[204:205], v[204:205], v[232:233]
	v_pk_add_f32 v[32:33], v[32:33], v[204:205]
	v_lshlrev_b32_e32 v232, 16, v223
	v_and_b32_e32 v233, 0xffff0000, v223
	v_pk_add_f32 v[206:207], v[206:207], v[232:233]
	v_pk_add_f32 v[34:35], v[34:35], v[206:207]
	global_store_dwordx4 v227, v[36:39], s[88:89] nt
	global_store_dwordx4 v227, v[32:35], s[88:89] offset:16 nt
	v_add_u32_e32 v224, 0x80200, v146
	v_lshrrev_b32_e32 v228, 1, v224
	global_load_dwordx4 v[176:179], v224, s[86:87]
	global_load_dwordx4 v[180:183], v224, s[86:87] offset:16
	global_load_dwordx4 v[208:211], v228, s[92:93]
	v_add_u32_e32 v225, 0x90200, v146
	v_lshrrev_b32_e32 v229, 1, v225
	global_load_dwordx4 v[184:187], v225, s[86:87]
	global_load_dwordx4 v[188:191], v225, s[86:87] offset:16
	global_load_dwordx4 v[212:215], v229, s[92:93]
	v_add_u32_e32 v226, 0xa0200, v146
	v_lshrrev_b32_e32 v230, 1, v226
	global_load_dwordx4 v[192:195], v226, s[86:87]
	global_load_dwordx4 v[196:199], v226, s[86:87] offset:16
	global_load_dwordx4 v[216:219], v230, s[92:93]
	v_add_u32_e32 v227, 0xb0200, v146
	v_lshrrev_b32_e32 v231, 1, v227
	global_load_dwordx4 v[200:203], v227, s[86:87]
	global_load_dwordx4 v[204:207], v227, s[86:87] offset:16
	global_load_dwordx4 v[220:223], v231, s[92:93]
	s_waitcnt vmcnt(0)
	v_lshlrev_b32_e32 v232, 16, v208
	v_and_b32_e32 v233, 0xffff0000, v208
	v_pk_add_f32 v[176:177], v[176:177], v[232:233]
	v_pk_add_f32 v[28:29], v[28:29], v[176:177]
	v_lshlrev_b32_e32 v232, 16, v209
	v_and_b32_e32 v233, 0xffff0000, v209
	v_pk_add_f32 v[178:179], v[178:179], v[232:233]
	v_pk_add_f32 v[30:31], v[30:31], v[178:179]
	v_lshlrev_b32_e32 v232, 16, v210
	v_and_b32_e32 v233, 0xffff0000, v210
	v_pk_add_f32 v[180:181], v[180:181], v[232:233]
	v_pk_add_f32 v[24:25], v[24:25], v[180:181]
	v_lshlrev_b32_e32 v232, 16, v211
	v_and_b32_e32 v233, 0xffff0000, v211
	v_pk_add_f32 v[182:183], v[182:183], v[232:233]
	v_pk_add_f32 v[26:27], v[26:27], v[182:183]
	global_store_dwordx4 v224, v[28:31], s[88:89] nt
	global_store_dwordx4 v224, v[24:27], s[88:89] offset:16 nt
	v_lshlrev_b32_e32 v232, 16, v212
	v_and_b32_e32 v233, 0xffff0000, v212
	v_pk_add_f32 v[184:185], v[184:185], v[232:233]
	v_pk_add_f32 v[20:21], v[20:21], v[184:185]
	v_lshlrev_b32_e32 v232, 16, v213
	v_and_b32_e32 v233, 0xffff0000, v213
	v_pk_add_f32 v[186:187], v[186:187], v[232:233]
	v_pk_add_f32 v[22:23], v[22:23], v[186:187]
	v_lshlrev_b32_e32 v232, 16, v214
	v_and_b32_e32 v233, 0xffff0000, v214
	v_pk_add_f32 v[188:189], v[188:189], v[232:233]
	v_pk_add_f32 v[16:17], v[16:17], v[188:189]
	v_lshlrev_b32_e32 v232, 16, v215
	v_and_b32_e32 v233, 0xffff0000, v215
	v_pk_add_f32 v[190:191], v[190:191], v[232:233]
	v_pk_add_f32 v[18:19], v[18:19], v[190:191]
	global_store_dwordx4 v225, v[20:23], s[88:89] nt
	global_store_dwordx4 v225, v[16:19], s[88:89] offset:16 nt
	v_lshlrev_b32_e32 v232, 16, v216
	v_and_b32_e32 v233, 0xffff0000, v216
	v_pk_add_f32 v[192:193], v[192:193], v[232:233]
	v_pk_add_f32 v[12:13], v[12:13], v[192:193]
	v_lshlrev_b32_e32 v232, 16, v217
	v_and_b32_e32 v233, 0xffff0000, v217
	v_pk_add_f32 v[194:195], v[194:195], v[232:233]
	v_pk_add_f32 v[14:15], v[14:15], v[194:195]
	v_lshlrev_b32_e32 v232, 16, v218
	v_and_b32_e32 v233, 0xffff0000, v218
	v_pk_add_f32 v[196:197], v[196:197], v[232:233]
	v_pk_add_f32 v[8:9], v[8:9], v[196:197]
	v_lshlrev_b32_e32 v232, 16, v219
	v_and_b32_e32 v233, 0xffff0000, v219
	v_pk_add_f32 v[198:199], v[198:199], v[232:233]
	v_pk_add_f32 v[10:11], v[10:11], v[198:199]
	global_store_dwordx4 v226, v[12:15], s[88:89] nt
	global_store_dwordx4 v226, v[8:11], s[88:89] offset:16 nt
	v_lshlrev_b32_e32 v232, 16, v220
	v_and_b32_e32 v233, 0xffff0000, v220
	v_pk_add_f32 v[200:201], v[200:201], v[232:233]
	v_pk_add_f32 v[4:5], v[4:5], v[200:201]
	v_lshlrev_b32_e32 v232, 16, v221
	v_and_b32_e32 v233, 0xffff0000, v221
	v_pk_add_f32 v[202:203], v[202:203], v[232:233]
	v_pk_add_f32 v[6:7], v[6:7], v[202:203]
	v_lshlrev_b32_e32 v232, 16, v222
	v_and_b32_e32 v233, 0xffff0000, v222
	v_pk_add_f32 v[204:205], v[204:205], v[232:233]
	v_pk_add_f32 v[0:1], v[0:1], v[204:205]
	v_lshlrev_b32_e32 v232, 16, v223
	v_and_b32_e32 v233, 0xffff0000, v223
	v_pk_add_f32 v[206:207], v[206:207], v[232:233]
	v_pk_add_f32 v[2:3], v[2:3], v[206:207]
	global_store_dwordx4 v227, v[4:7], s[88:89] nt
	global_store_dwordx4 v227, v[0:3], s[88:89] offset:16 nt
	s_andn2_b64 vcc, exec, s[2:3]
	s_mov_b64 s[2:3], -1
	s_cbranch_vccnz .LBB0_1227
	s_andn2_b64 vcc, exec, s[20:21]
	s_cbranch_vccnz .LBB0_1226
	s_barrier
	s_branch .LBB0_1226

; __global__ void __launch_bounds__(NTHR) mega(Args a) {
	.amdhsa_kernel _Z4mega4Args
		.amdhsa_group_segment_fixed_size 0
		.amdhsa_private_segment_fixed_size 0
		.amdhsa_kernarg_size 536
		.amdhsa_user_sgpr_count 2
		.amdhsa_user_sgpr_dispatch_ptr 0
		.amdhsa_user_sgpr_queue_ptr 0
		.amdhsa_user_sgpr_kernarg_segment_ptr 1
		.amdhsa_user_sgpr_dispatch_id 0
		.amdhsa_user_sgpr_kernarg_preload_length 0
		.amdhsa_user_sgpr_kernarg_preload_offset 0
		.amdhsa_user_sgpr_private_segment_size 0
		.amdhsa_uses_dynamic_stack 0
		.amdhsa_enable_private_segment 0
		.amdhsa_system_sgpr_workgroup_id_x 1
		.amdhsa_system_sgpr_workgroup_id_y 0
		.amdhsa_system_sgpr_workgroup_id_z 0
		.amdhsa_system_sgpr_workgroup_info 0
		.amdhsa_system_vgpr_workitem_id 2
		.amdhsa_next_free_vgpr 252
		.amdhsa_next_free_sgpr 94
		.amdhsa_accum_offset 252
		.amdhsa_reserve_vcc 1
		.amdhsa_float_round_mode_32 0
		.amdhsa_float_round_mode_16_64 0
		.amdhsa_float_denorm_mode_32 3
		.amdhsa_float_denorm_mode_16_64 3
		.amdhsa_dx10_clamp 1
		.amdhsa_ieee_mode 1
		.amdhsa_fp16_overflow 0
		.amdhsa_tg_split 0
		.amdhsa_exception_fp_ieee_invalid_op 0
		.amdhsa_exception_fp_denorm_src 0
		.amdhsa_exception_fp_ieee_div_zero 0
		.amdhsa_exception_fp_ieee_overflow 0
		.amdhsa_exception_fp_ieee_underflow 0
		.amdhsa_exception_fp_ieee_inexact 0
		.amdhsa_exception_int_div_zero 0
	.end_amdhsa_kernel

; __global__ void __launch_bounds__(NTHR) mega(Args a) {
amdhsa.kernels:
  - .agpr_count:     0
    .args:
      - .offset:         0
        .size:           280
        .value_kind:     by_value
      - .offset:         280
        .size:           4
        .value_kind:     hidden_block_count_x
      - .offset:         284
        .size:           4
        .value_kind:     hidden_block_count_y
      - .offset:         288
        .size:           4
        .value_kind:     hidden_block_count_z
      - .offset:         292
        .size:           2
        .value_kind:     hidden_group_size_x
      - .offset:         294
        .size:           2
        .value_kind:     hidden_group_size_y
      - .offset:         296
        .size:           2
        .value_kind:     hidden_group_size_z
      - .offset:         298
        .size:           2
        .value_kind:     hidden_remainder_x
      - .offset:         300
        .size:           2
        .value_kind:     hidden_remainder_y
      - .offset:         302
        .size:           2
        .value_kind:     hidden_remainder_z
      - .offset:         320
        .size:           8
        .value_kind:     hidden_global_offset_x
      - .offset:         328
        .size:           8
        .value_kind:     hidden_global_offset_y
      - .offset:         336
        .size:           8
        .value_kind:     hidden_global_offset_z
      - .offset:         344
        .size:           2
        .value_kind:     hidden_grid_dims
      - .offset:         368
        .size:           8
        .value_kind:     hidden_multigrid_sync_arg
      - .offset:         400
        .size:           4
        .value_kind:     hidden_dynamic_lds_size
    .group_segment_fixed_size: 0
    .kernarg_segment_align: 8
    .kernarg_segment_size: 536
    .language:       OpenCL C
    .language_version:
      - 2
      - 0
    .max_flat_workgroup_size: 512
    .name:           _Z4mega4Args
    .private_segment_fixed_size: 0
    .sgpr_count:     100
    .sgpr_spill_count: 0
    .symbol:         _Z4mega4Args.kd
    .uniform_work_group_size: 1
    .uses_dynamic_stack: false
    .vgpr_count:     252
    .vgpr_spill_count: 0
    .wavefront_size: 64
